# lever 4 mirror: static s_setprio 1 for waves 0-3 (older half) per GEMM phase instead of waves 4-7
# speedup vs baseline: 1.0028x; 1.0007x over previous
; #define PG8_STAGE(bufoff, gbase, voff) do { _Pragma("unroll") for (int _i = 0; _i < 2; ++_i) \
;         __builtin_amdgcn_global_load_lds((const unsigned*)((const char*)(gbase) + (voff)[_i]), (LAS unsigned*)(lds + (bufoff) + ldsw + _i * 8192), 16, 0, 0); } while (0)
; #define PG8_WAIT_V(n) asm volatile("s_waitcnt vmcnt(" #n ")" ::: "memory")
; #define PG8_BAR __builtin_amdgcn_s_barrier()
; template <class Epi, class Sched>
; __device__ __forceinline__ void gemm_phase(LAS unsigned char* lds, const Gemm g, const Sched& S, const Epi& E, const int tid) {
;     const int wid = __builtin_amdgcn_readfirstlane(tid >> 6), lane = tid & 63, wr = wid >> 2, wc = wid & 3, fr = lane & 15, fq = lane >> 4;
;     const int K = g.K, nt = K / BK;
;     unsigned voffA[2], voffB[2];
; #pragma unroll
;     for (int i = 0; i < 2; ++i) { int R, C; stage_rc(tid * 16 + i * 8192, R, C); const int Rb = Epi::PERM ? ((R & ~31) + perm32(R & 31)) : R;
;         voffA[i] = (unsigned)(R * K + C) * 2u; voffB[i] = (unsigned)(Rb * K + C) * 2u; }
;     const size_t kstep = (size_t)(BK * 2);
;     const size_t hstep = (size_t)HALF * K * 2;
;     const size_t tstep = 2 * hstep;
;     const unsigned ldsw = (unsigned)wid * 1024u;
;     const int aoff = lds_byte(wr * 64 + fr, fq * 8), boff = lds_byte(wc * 32 + fr, fq * 8);
;     ...
;     Unit cur, nxt; int ui = 0;
;     if (!S.next(0, cur)) return;
;     f32x4 acc[2][2][4][2];
; #pragma unroll
;     for (int a = 0; a < 2; ++a)
; #pragma unroll
;         for (int b = 0; b < 2; ++b)
; #pragma unroll
;             for (int m = 0; m < 4; ++m)
; #pragma unroll
;                 for (int n = 0; n < 2; ++n) acc[a][b][m][n] = (f32x4){0.f, 0.f, 0.f, 0.f};
;     bf16x8 At[4][2], B0[2][2], B1[2][2];
;     const char* cA = (const char*)g.A + (size_t)cur.pm * tstep; const char* cB = (const char*)g.Bt + (size_t)cur.pn * tstep;
;     PG8_STAGE(PG8_SB(0, 0), cB, voffB); PG8_STAGE(PG8_SB(0, 1), cB + hstep, voffB); PG8_STAGE(PG8_SA(0, 0), cA, voffA); PG8_STAGE(PG8_SA(0, 1), cA + hstep, voffA);
;     if (wr == 1) PG8_BAR;
;     PG8_WAIT_V(2); PG8_BAR;
;     PG8_STAGE(PG8_SB(1, 0), cB + kstep, voffB); PG8_STAGE(PG8_SA(1, 0), cA + kstep, voffA); PG8_STAGE(PG8_SB(1, 1), cB + hstep + kstep, voffB);
;     PG8_WAIT_V(6); PG8_BAR;
.LBB0_155:
	s_cmp_eq_u32 s14, 1
	s_cselect_b64 s[10:11], -1, 0
	s_cmp_lg_u32 s14, 1
	s_cselect_b64 s[0:1], -1, 0
	s_cmp_ge_i32 s72, s28
	v_writelane_b32 v255, s0, 15
	s_cselect_b64 s[48:49], -1, 0
	s_cmp_lt_i32 s72, s29
	v_writelane_b32 v255, s1, 16
	s_cselect_b64 s[0:1], -1, 0
	s_and_b64 s[4:5], s[48:49], s[0:1]
	v_cndmask_b32_e64 v0, 0, 1, s[4:5]
	s_mov_b64 s[0:1], -1
	s_and_b64 vcc, exec, s[10:11]
	v_cmp_ne_u32_e64 s[8:9], 1, v0
	s_cbranch_vccnz .LBB0_249
	s_and_b64 vcc, exec, s[8:9]
	s_cbranch_vccnz .LBB0_177
	v_readlane_b32 s0, v252, 56
	s_waitcnt vmcnt(0)
	v_mov_b32_e32 v132, v223
	v_readlane_b32 s1, v252, 57
	s_andn2_b64 vcc, exec, s[0:1]
	v_readfirstlane_b32 s6, v132
	s_cbranch_vccnz .LBB0_177
	s_cmp_lg_u32 s14, 0
	s_cselect_b64 s[4:5], -1, 0
	v_cndmask_b32_e64 v0, 0, 1, s[4:5]
	v_readlane_b32 s1, v254, 51
	v_readfirstlane_b32 s0, v0
	v_lshlrev_b32_e32 v0, 4, v132
	s_waitcnt lgkmcnt(0)
	v_add_u32_e32 v1, 0x2000, v0
	v_ashrrev_i32_e32 v2, 31, v1
	v_lshrrev_b32_e32 v2, 22, v2
	v_add_u32_e32 v2, v1, v2
	s_waitcnt vmcnt(1)
	v_ashrrev_i32_e32 v4, 10, v2
	v_mul_i32_i24_e32 v2, 0x400, v4
	v_sub_u32_e32 v1, v1, v2
	v_lshrrev_b32_e32 v2, 4, v1
	v_bitop3_b32 v1, v2, v1, 32 bitop3:0x6c
	v_ashrrev_i32_e32 v2, 31, v1
	s_or_b32 s0, s1, s0
	v_lshrrev_b32_e32 v2, 26, v2
	s_mul_i32 s12, s0, 0x580000
	v_add_u32_e32 v2, v1, v2
	v_lshlrev_b32_e32 v3, 3, v4
	s_lshl_b64 s[0:1], s[12:13], 1
	v_readlane_b32 s3, v252, 26
	v_ashrrev_i32_e32 v5, 6, v2
	v_and_b32_e32 v3, -16, v3
	s_add_u32 s12, s3, s0
	v_readlane_b32 s0, v252, 27
	v_add_u32_e32 v3, v5, v3
	s_addc_u32 s73, s0, s1
	v_and_b32_e32 v6, 3, v5
	s_mov_b32 s0, 0x1fffe0
	v_lshrrev_b32_e32 v7, 2, v3
	v_lshlrev_b32_e32 v8, 1, v3
	v_and_b32_e32 v2, 0xc0, v2
	v_and_or_b32 v6, v3, s0, v6
	v_and_b32_e32 v7, 4, v7
	v_and_b32_e32 v8, 24, v8
	v_sub_u32_e32 v1, v1, v2
	v_mov_b32_e32 v11, 1
	v_or3_b32 v7, v6, v7, v8
	v_lshlrev_b32_e32 v6, 5, v4
	v_ashrrev_i16_sdwa v1, v11, sext(v1) dst_sel:DWORD dst_unused:UNUSED_PAD src0_sel:DWORD src1_sel:BYTE_0
	v_and_b32_e32 v8, 32, v6
	v_bfe_i32 v6, v1, 0, 16
	v_add_lshl_u32 v1, v8, v6, 1
	v_lshl_add_u32 v134, v7, 11, v1
	v_lshl_add_u32 v136, v3, 11, v1
	v_bfe_i32 v1, v132, 27, 1
	v_lshrrev_b32_e32 v1, 22, v1
	v_add_u32_e32 v1, v0, v1
	v_and_b32_e32 v1, 0xfffffc00, v1
	v_sub_u32_e32 v0, v0, v1
	v_lshrrev_b32_e32 v1, 4, v0
	v_ashrrev_i32_e32 v133, 31, v132
	v_bitop3_b32 v0, v1, v0, 32 bitop3:0x6c
	v_lshrrev_b32_e32 v2, 26, v133
	v_ashrrev_i32_e32 v1, 31, v0
	v_add_u32_e32 v2, v132, v2
	v_lshrrev_b32_e32 v1, 26, v1
	v_ashrrev_i32_e32 v8, 6, v2
	v_add_u32_e32 v1, v0, v1
	v_lshlrev_b32_e32 v2, 3, v8
	v_ashrrev_i32_e32 v7, 6, v1
	v_and_b32_e32 v2, -16, v2
	v_add_u32_e32 v2, v7, v2
	v_and_b32_e32 v3, 3, v7
	v_and_or_b32 v3, v2, s0, v3
	v_readlane_b32 s0, v252, 61
	v_lshrrev_b32_e32 v9, 2, v2
	v_lshlrev_b32_e32 v10, 1, v2
	v_and_b32_e32 v1, 0xc0, v1
	v_readlane_b32 s1, v252, 62
	s_add_u32 s66, s12, s0
	v_and_b32_e32 v9, 4, v9
	v_and_b32_e32 v10, 24, v10
	v_sub_u32_e32 v0, v0, v1
	s_addc_u32 s67, s73, s1
	s_ashr_i32 s22, s6, 6
	v_or3_b32 v3, v3, v9, v10
	v_lshlrev_b32_e32 v9, 5, v8
	v_ashrrev_i16_sdwa v0, v11, sext(v0) dst_sel:DWORD dst_unused:UNUSED_PAD src0_sel:DWORD src1_sel:BYTE_0
	s_ashr_i32 s7, s6, 8
	s_lshl_b32 s74, s22, 10
	v_and_b32_e32 v10, 32, v9
	v_bfe_i32 v9, v0, 0, 16
	s_add_u32 s0, s66, 0x40000
	v_add_lshl_u32 v0, v10, v9, 1
	s_addc_u32 s1, s67, 0
	s_add_i32 s75, s74, 0
	v_lshl_add_u32 v192, v3, 11, v0
	s_add_i32 m0, s75, 0x10000
	v_lshl_add_u32 v138, v2, 11, v0
	global_load_lds_dwordx4 v192, s[66:67]
	s_add_i32 m0, s75, 0x12000
	s_add_i32 s81, s75, 0x2000
	global_load_lds_dwordx4 v134, s[66:67]
	s_add_i32 m0, s75, 0x14000
	s_add_i32 s82, s75, 0x4000
	global_load_lds_dwordx4 v192, s[0:1]
	s_add_i32 m0, s75, 0x16000
	s_add_i32 s83, s75, 0x6000
	global_load_lds_dwordx4 v134, s[0:1]
	v_readlane_b32 s0, v252, 63
	s_mov_b32 m0, s75
	v_readlane_b32 s1, v253, 0
	v_mov_b32_e32 v135, v193
	s_cmp_eq_u32 s7, 1
	v_lshl_add_u64 v[0:1], s[66:67], 0, v[192:193]
	v_lshl_add_u64 v[2:3], s[66:67], 0, v[134:135]
	s_nop 0
	global_load_lds_dwordx4 v138, s[0:1]
	s_mov_b32 m0, s81
	s_nop 0
	global_load_lds_dwordx4 v136, s[0:1]
	v_readlane_b32 s0, v253, 1
	s_mov_b32 m0, s82
	v_readlane_b32 s1, v253, 2
	s_nop 4
	global_load_lds_dwordx4 v138, s[0:1]
	s_mov_b32 m0, s83
	s_nop 0
	global_load_lds_dwordx4 v136, s[0:1]
	s_cselect_b64 s[0:1], -1, 0
	s_setprio 1
	s_cmp_lg_u32 s7, 1
	s_cbranch_scc1 .LBB0_160
	s_barrier
	s_setprio 0

; #define PG8_STAGE(bufoff, gbase, voff) do { _Pragma("unroll") for (int _i = 0; _i < 2; ++_i) \
;         __builtin_amdgcn_global_load_lds((const unsigned*)((const char*)(gbase) + (voff)[_i]), (LAS unsigned*)(lds + (bufoff) + ldsw + _i * 8192), 16, 0, 0); } while (0)
; #define PG8_WAIT_V(n) asm volatile("s_waitcnt vmcnt(" #n ")" ::: "memory")
; #define PG8_BAR __builtin_amdgcn_s_barrier()
; template <class Epi, class Sched>
; __device__ __forceinline__ void gemm_phase(LAS unsigned char* lds, const Gemm g, const Sched& S, const Epi& E, const int tid) {
;     const int wid = __builtin_amdgcn_readfirstlane(tid >> 6), lane = tid & 63, wr = wid >> 2, wc = wid & 3, fr = lane & 15, fq = lane >> 4;
;     const int K = g.K, nt = K / BK;
;     unsigned voffA[2], voffB[2];
; #pragma unroll
;     for (int i = 0; i < 2; ++i) { int R, C; stage_rc(tid * 16 + i * 8192, R, C); const int Rb = Epi::PERM ? ((R & ~31) + perm32(R & 31)) : R;
;         voffA[i] = (unsigned)(R * K + C) * 2u; voffB[i] = (unsigned)(Rb * K + C) * 2u; }
;     const size_t kstep = (size_t)(BK * 2);
;     const size_t hstep = (size_t)HALF * K * 2;
;     const size_t tstep = 2 * hstep;
;     const unsigned ldsw = (unsigned)wid * 1024u;
;     const int aoff = lds_byte(wr * 64 + fr, fq * 8), boff = lds_byte(wc * 32 + fr, fq * 8);
;     ...
;     Unit cur, nxt; int ui = 0;
;     if (!S.next(0, cur)) return;
;     f32x4 acc[2][2][4][2];
; #pragma unroll
;     for (int a = 0; a < 2; ++a)
; #pragma unroll
;         for (int b = 0; b < 2; ++b)
; #pragma unroll
;             for (int m = 0; m < 4; ++m)
; #pragma unroll
;                 for (int n = 0; n < 2; ++n) acc[a][b][m][n] = (f32x4){0.f, 0.f, 0.f, 0.f};
;     bf16x8 At[4][2], B0[2][2], B1[2][2];
;     const char* cA = (const char*)g.A + (size_t)cur.pm * tstep; const char* cB = (const char*)g.Bt + (size_t)cur.pn * tstep;
;     PG8_STAGE(PG8_SB(0, 0), cB, voffB); PG8_STAGE(PG8_SB(0, 1), cB + hstep, voffB); PG8_STAGE(PG8_SA(0, 0), cA, voffA); PG8_STAGE(PG8_SA(0, 1), cA + hstep, voffA);
;     if (wr == 1) PG8_BAR;
;     PG8_WAIT_V(2); PG8_BAR;
;     PG8_STAGE(PG8_SB(1, 0), cB + kstep, voffB); PG8_STAGE(PG8_SA(1, 0), cA + kstep, voffA); PG8_STAGE(PG8_SB(1, 1), cB + hstep + kstep, voffB);
;     PG8_WAIT_V(6); PG8_BAR;
.LBB0_249:
	s_and_b64 vcc, exec, s[0:1]
	s_cbranch_vccz .LBB0_542
	s_and_b64 vcc, exec, s[8:9]
	s_cbranch_vccnz .LBB0_335
	v_mov_b32_e32 v160, v223
	s_waitcnt vmcnt(0)
	v_mov_b32_e32 v6, 1
	s_waitcnt lgkmcnt(5)
	v_ashrrev_i32_e32 v161, 31, v160
	s_waitcnt lgkmcnt(0)
	v_lshrrev_b32_e32 v1, 26, v161
	v_add_u32_e32 v1, v160, v1
	s_waitcnt lgkmcnt(0)
	v_ashrrev_i32_e32 v171, 6, v1
	v_bfe_i32 v1, v160, 27, 1
	v_lshlrev_b32_e32 v0, 4, v160
	v_lshrrev_b32_e32 v1, 22, v1
	v_add_u32_e32 v1, v0, v1
	v_and_b32_e32 v1, 0xfffffc00, v1
	v_sub_u32_e32 v1, v0, v1
	v_lshrrev_b32_e32 v2, 4, v1
	v_bitop3_b32 v1, v2, v1, 32 bitop3:0x6c
	v_ashrrev_i32_e32 v3, 31, v1
	v_lshrrev_b32_e32 v3, 26, v3
	v_add_u32_e32 v3, v1, v3
	v_lshlrev_b32_e32 v2, 3, v171
	v_ashrrev_i32_e32 v173, 6, v3
	v_and_b32_e32 v3, 0xc0, v3
	v_and_b32_e32 v2, -16, v2
	v_sub_u32_e32 v1, v1, v3
	v_add_u32_e32 v2, v173, v2
	v_ashrrev_i16_sdwa v1, v6, sext(v1) dst_sel:DWORD dst_unused:UNUSED_PAD src0_sel:DWORD src1_sel:BYTE_0
	v_lshlrev_b32_e32 v4, 5, v171
	v_bfe_i32 v210, v1, 0, 16
	v_lshlrev_b32_e32 v1, 1, v2
	v_lshrrev_b32_e32 v3, 2, v2
	v_and_b32_e32 v5, 3, v173
	s_mov_b32 s0, 0x1fffe0
	v_and_b32_e32 v4, 32, v4
	v_and_b32_e32 v1, 24, v1
	v_and_b32_e32 v3, 4, v3
	v_and_or_b32 v5, v2, s0, v5
	v_or3_b32 v1, v5, v3, v1
	v_add_lshl_u32 v3, v4, v210, 1
	v_add_u32_e32 v0, 0x2000, v0
	v_lshl_add_u32 v164, v1, 11, v3
	v_ashrrev_i32_e32 v1, 31, v0
	v_lshrrev_b32_e32 v1, 22, v1
	v_add_u32_e32 v1, v0, v1
	v_ashrrev_i32_e32 v211, 10, v1
	v_mul_i32_i24_e32 v1, 0x400, v211
	v_sub_u32_e32 v0, v0, v1
	v_lshrrev_b32_e32 v1, 4, v0
	v_bitop3_b32 v0, v1, v0, 32 bitop3:0x6c
	v_lshl_add_u32 v162, v2, 11, v3
	v_ashrrev_i32_e32 v2, 31, v0
	v_lshrrev_b32_e32 v2, 26, v2
	v_add_u32_e32 v2, v0, v2
	v_lshlrev_b32_e32 v1, 3, v211
	v_ashrrev_i32_e32 v212, 6, v2
	v_and_b32_e32 v2, 0xc0, v2
	v_and_b32_e32 v1, -16, v1
	v_sub_u32_e32 v0, v0, v2
	v_add_u32_e32 v1, v212, v1
	v_ashrrev_i16_sdwa v0, v6, sext(v0) dst_sel:DWORD dst_unused:UNUSED_PAD src0_sel:DWORD src1_sel:BYTE_0
	v_lshlrev_b32_e32 v3, 5, v211
	v_bfe_i32 v213, v0, 0, 16
	v_lshlrev_b32_e32 v0, 1, v1
	v_lshrrev_b32_e32 v2, 2, v1
	v_and_b32_e32 v4, 3, v212
	v_and_b32_e32 v3, 32, v3
	v_and_b32_e32 v0, 24, v0
	v_and_b32_e32 v2, 4, v2
	v_and_or_b32 v4, v1, s0, v4
	v_or3_b32 v0, v4, v2, v0
	v_add_lshl_u32 v2, v3, v213, 1
	v_readlane_b32 s0, v253, 46
	v_lshl_add_u32 v168, v0, 11, v2
	v_and_b32_e32 v214, 15, v160
	v_lshlrev_b32_e32 v0, 2, v160
	v_readlane_b32 s1, v253, 47
	v_readfirstlane_b32 s4, v160
	v_lshl_add_u32 v166, v1, 11, v2
	v_lshlrev_b32_e32 v170, 6, v214
	s_andn2_b64 vcc, exec, s[0:1]
	v_and_b32_e32 v215, 32, v0
	s_cbranch_vccnz .LBB0_311
	s_ashr_i32 s5, s4, 6
	s_lshl_b32 s12, s5, 10
	s_add_i32 s73, s12, 0
	v_readlane_b32 s0, v255, 5
	s_add_i32 m0, s73, 0x10000
	v_readlane_b32 s1, v255, 6
	s_add_i32 s74, s73, 0x2000
	s_add_i32 s75, s73, 0x4000
	s_add_i32 s81, s73, 0x6000
	s_ashr_i32 s6, s4, 8
	s_nop 0
	global_load_lds_dwordx4 v164, s[0:1]
	s_add_i32 m0, s73, 0x12000
	s_nop 0
	global_load_lds_dwordx4 v168, s[0:1]
	v_readlane_b32 s0, v255, 3
	s_add_i32 m0, s73, 0x14000
	v_readlane_b32 s1, v255, 4
	s_nop 4
	global_load_lds_dwordx4 v164, s[0:1]
	s_add_i32 m0, s73, 0x16000
	s_cmp_eq_u32 s6, 1
	global_load_lds_dwordx4 v168, s[0:1]
	v_readlane_b32 s0, v254, 22
	s_mov_b32 m0, s73
	v_readlane_b32 s1, v254, 23
	s_nop 4
	global_load_lds_dwordx4 v162, s[0:1]
	s_mov_b32 m0, s74
	s_nop 0
	global_load_lds_dwordx4 v166, s[0:1]
	v_readlane_b32 s0, v254, 24
	s_mov_b32 m0, s75
	v_readlane_b32 s1, v254, 25
	s_nop 4
	global_load_lds_dwordx4 v162, s[0:1]
	s_mov_b32 m0, s81
	s_nop 0
	global_load_lds_dwordx4 v166, s[0:1]
	s_cselect_b64 s[0:1], -1, 0
	s_setprio 1
	s_cmp_lg_u32 s6, 1
	s_cbranch_scc1 .LBB0_254
	s_barrier
	s_setprio 0

; #define PG8_STAGE(bufoff, gbase, voff) do { _Pragma("unroll") for (int _i = 0; _i < 2; ++_i) \
;         __builtin_amdgcn_global_load_lds((const unsigned*)((const char*)(gbase) + (voff)[_i]), (LAS unsigned*)(lds + (bufoff) + ldsw + _i * 8192), 16, 0, 0); } while (0)
; #define PG8_WAIT_V(n) asm volatile("s_waitcnt vmcnt(" #n ")" ::: "memory")
; #define PG8_BAR __builtin_amdgcn_s_barrier()
; template <class Epi, class Sched>
; __device__ __forceinline__ void gemm_phase(LAS unsigned char* lds, const Gemm g, const Sched& S, const Epi& E, const int tid) {
;     ...
;     const char* cA = (const char*)g.A + (size_t)cur.pm * tstep; const char* cB = (const char*)g.Bt + (size_t)cur.pn * tstep;
;     PG8_STAGE(PG8_SB(0, 0), cB, voffB); PG8_STAGE(PG8_SB(0, 1), cB + hstep, voffB); PG8_STAGE(PG8_SA(0, 0), cA, voffA); PG8_STAGE(PG8_SA(0, 1), cA + hstep, voffA);
;     if (wr == 1) PG8_BAR;
;     PG8_WAIT_V(2); PG8_BAR;
;     PG8_STAGE(PG8_SB(1, 0), cB + kstep, voffB); PG8_STAGE(PG8_SA(1, 0), cA + kstep, voffA); PG8_STAGE(PG8_SB(1, 1), cB + hstep + kstep, voffB);
;     PG8_WAIT_V(6); PG8_BAR;
.LBB0_311:
	v_readlane_b32 s0, v253, 48
	v_readlane_b32 s1, v253, 49
	s_andn2_b64 vcc, exec, s[0:1]
	v_readfirstlane_b32 s4, v160
	s_cbranch_vccnz .LBB0_335
	s_ashr_i32 s6, s4, 6
	s_lshl_b32 s52, s6, 10
	s_add_i32 s53, s52, 0
	v_readlane_b32 s0, v254, 35
	s_add_i32 m0, s53, 0x10000
	v_readlane_b32 s1, v254, 36
	s_add_i32 s56, s53, 0x2000
	s_add_i32 s57, s53, 0x4000
	s_add_i32 s58, s53, 0x6000
	s_ashr_i32 s5, s4, 8
	s_nop 0
	global_load_lds_dwordx4 v164, s[0:1]
	s_add_i32 m0, s53, 0x12000
	s_nop 0
	global_load_lds_dwordx4 v168, s[0:1]
	v_readlane_b32 s0, v254, 33
	s_add_i32 m0, s53, 0x14000
	v_readlane_b32 s1, v254, 34
	s_nop 4
	global_load_lds_dwordx4 v164, s[0:1]
	s_add_i32 m0, s53, 0x16000
	s_cmp_eq_u32 s5, 1
	global_load_lds_dwordx4 v168, s[0:1]
	v_readlane_b32 s0, v255, 9
	s_mov_b32 m0, s53
	v_readlane_b32 s1, v255, 10
	s_nop 4
	global_load_lds_dwordx4 v162, s[0:1]
	s_mov_b32 m0, s56
	s_nop 0
	global_load_lds_dwordx4 v166, s[0:1]
	v_readlane_b32 s0, v255, 11
	s_mov_b32 m0, s57
	v_readlane_b32 s1, v255, 12
	s_nop 4
	global_load_lds_dwordx4 v162, s[0:1]
	s_mov_b32 m0, s58
	s_nop 0
	global_load_lds_dwordx4 v166, s[0:1]
	s_cselect_b64 s[0:1], -1, 0
	s_setprio 1
	s_cmp_lg_u32 s5, 1
	s_cbranch_scc1 .LBB0_314
	s_barrier
	s_setprio 0

; #define PG8_STAGE(bufoff, gbase, voff) do { _Pragma("unroll") for (int _i = 0; _i < 2; ++_i) \
;         __builtin_amdgcn_global_load_lds((const unsigned*)((const char*)(gbase) + (voff)[_i]), (LAS unsigned*)(lds + (bufoff) + ldsw + _i * 8192), 16, 0, 0); } while (0)
; #define PG8_WAIT_V(n) asm volatile("s_waitcnt vmcnt(" #n ")" ::: "memory")
; #define PG8_BAR __builtin_amdgcn_s_barrier()
; template <class Epi, class Sched>
; __device__ __forceinline__ void gemm_phase(LAS unsigned char* lds, const Gemm g, const Sched& S, const Epi& E, const int tid) {
;     const int wid = __builtin_amdgcn_readfirstlane(tid >> 6), lane = tid & 63, wr = wid >> 2, wc = wid & 3, fr = lane & 15, fq = lane >> 4;
;     const int K = g.K, nt = K / BK;
;     unsigned voffA[2], voffB[2];
; #pragma unroll
;     for (int i = 0; i < 2; ++i) { int R, C; stage_rc(tid * 16 + i * 8192, R, C); const int Rb = Epi::PERM ? ((R & ~31) + perm32(R & 31)) : R;
;         voffA[i] = (unsigned)(R * K + C) * 2u; voffB[i] = (unsigned)(Rb * K + C) * 2u; }
;     const size_t kstep = (size_t)(BK * 2);
;     const size_t hstep = (size_t)HALF * K * 2;
;     const size_t tstep = 2 * hstep;
;     const unsigned ldsw = (unsigned)wid * 1024u;
;     const int aoff = lds_byte(wr * 64 + fr, fq * 8), boff = lds_byte(wc * 32 + fr, fq * 8);
;     ...
;     Unit cur, nxt; int ui = 0;
;     if (!S.next(0, cur)) return;
;     f32x4 acc[2][2][4][2];
; #pragma unroll
;     for (int a = 0; a < 2; ++a)
; #pragma unroll
;         for (int b = 0; b < 2; ++b)
; #pragma unroll
;             for (int m = 0; m < 4; ++m)
; #pragma unroll
;                 for (int n = 0; n < 2; ++n) acc[a][b][m][n] = (f32x4){0.f, 0.f, 0.f, 0.f};
;     bf16x8 At[4][2], B0[2][2], B1[2][2];
;     const char* cA = (const char*)g.A + (size_t)cur.pm * tstep; const char* cB = (const char*)g.Bt + (size_t)cur.pn * tstep;
;     PG8_STAGE(PG8_SB(0, 0), cB, voffB); PG8_STAGE(PG8_SB(0, 1), cB + hstep, voffB); PG8_STAGE(PG8_SA(0, 0), cA, voffA); PG8_STAGE(PG8_SA(0, 1), cA + hstep, voffA);
;     if (wr == 1) PG8_BAR;
;     PG8_WAIT_V(2); PG8_BAR;
;     PG8_STAGE(PG8_SB(1, 0), cB + kstep, voffB); PG8_STAGE(PG8_SA(1, 0), cA + kstep, voffA); PG8_STAGE(PG8_SB(1, 1), cB + hstep + kstep, voffB);
;     PG8_WAIT_V(6); PG8_BAR;
.LBB0_546:
	v_readlane_b32 s6, v254, 13
	v_readlane_b32 s7, v254, 14
	s_andn2_b64 vcc, exec, s[6:7]
	v_readfirstlane_b32 s4, v229
	s_cbranch_vccnz .LBB0_676
	v_lshlrev_b32_e32 v230, 4, v229
	v_add_u32_e32 v0, 0x2000, v230
	s_waitcnt lgkmcnt(0)
	v_ashrrev_i32_e32 v1, 31, v0
	v_lshrrev_b32_e32 v1, 22, v1
	v_add_u32_e32 v1, v0, v1
	v_ashrrev_i32_e32 v1, 10, v1
	v_mul_i32_i24_e32 v2, 0x400, v1
	v_sub_u32_e32 v0, v0, v2
	v_lshrrev_b32_e32 v2, 4, v0
	v_bitop3_b32 v0, v2, v0, 32 bitop3:0x6c
	v_ashrrev_i32_e32 v2, 31, v0
	v_lshrrev_b32_e32 v2, 26, v2
	v_add_u32_e32 v2, v0, v2
	s_waitcnt vmcnt(0)
	v_lshlrev_b32_e32 v4, 3, v1
	v_ashrrev_i32_e32 v3, 6, v2
	v_and_b32_e32 v4, -16, v4
	v_lshlrev_b32_e32 v1, 5, v1
	v_add_u32_e32 v4, v3, v4
	v_and_b32_e32 v12, 32, v1
	v_and_b32_e32 v1, 0xc0, v2
	v_and_b32_e32 v3, 3, v3
	s_mov_b32 s3, 0x7fffffe0
	v_lshrrev_b32_e32 v5, 2, v4
	v_lshlrev_b32_e32 v6, 1, v4
	v_sub_u32_e32 v0, v0, v1
	v_mov_b32_e32 v7, 1
	v_and_or_b32 v3, v4, s3, v3
	v_and_b32_e32 v5, 4, v5
	v_and_b32_e32 v6, 24, v6
	v_ashrrev_i16_sdwa v0, v7, sext(v0) dst_sel:DWORD dst_unused:UNUSED_PAD src0_sel:DWORD src1_sel:BYTE_0
	v_or3_b32 v3, v3, v5, v6
	v_bfe_i32 v13, v0, 0, 16
	v_mul_lo_u32 v3, s5, v3
	v_add_u32_e32 v0, v12, v13
	v_mul_lo_u32 v14, s5, v4
	s_waitcnt lgkmcnt(6)
	v_add_lshl_u32 v198, v3, v0, 1
	s_waitcnt lgkmcnt(5)
	v_add_lshl_u32 v200, v14, v0, 1
	v_bfe_i32 v0, v229, 27, 1
	v_lshrrev_b32_e32 v0, 22, v0
	v_add_u32_e32 v0, v230, v0
	v_and_b32_e32 v0, 0xfffffc00, v0
	v_sub_u32_e32 v0, v230, v0
	v_lshrrev_b32_e32 v1, 4, v0
	v_ashrrev_i32_e32 v3, 31, v229
	v_bitop3_b32 v0, v1, v0, 32 bitop3:0x6c
	v_lshrrev_b32_e32 v3, 26, v3
	v_ashrrev_i32_e32 v1, 31, v0
	v_add_u32_e32 v3, v229, v3
	s_ashr_i32 s7, s4, 6
	v_lshrrev_b32_e32 v1, 26, v1
	v_ashrrev_i32_e32 v3, 6, v3
	s_ashr_i32 s6, s4, 8
	s_lshl_b32 s12, s5, 8
	s_lshl_b32 s93, s5, 9
	s_lshl_b32 s94, s7, 10
	v_add_u32_e32 v1, v0, v1
	v_lshlrev_b32_e32 v4, 3, v3
	s_and_b64 s[8:9], exec, s[10:11]
	v_ashrrev_i32_e32 v2, 6, v1
	v_and_b32_e32 v4, -16, v4
	v_add_u32_e32 v4, v2, v4
	v_and_b32_e32 v1, 0xc0, v1
	v_readlane_b32 s8, v254, 26
	v_and_b32_e32 v2, 3, v2
	v_lshrrev_b32_e32 v5, 2, v4
	v_lshlrev_b32_e32 v6, 1, v4
	v_sub_u32_e32 v0, v0, v1
	v_readlane_b32 s9, v254, 27
	s_mov_b32 s22, s8
	v_and_or_b32 v2, v4, s3, v2
	v_and_b32_e32 v5, 4, v5
	v_and_b32_e32 v6, 24, v6
	v_lshlrev_b32_e32 v3, 5, v3
	v_ashrrev_i16_sdwa v0, v7, sext(v0) dst_sel:DWORD dst_unused:UNUSED_PAD src0_sel:DWORD src1_sel:BYTE_0
	s_mul_i32 s9, s93, s22
	s_cselect_b32 s95, s65, s17
	s_cselect_b32 s96, s64, s16
	v_or3_b32 v2, v2, v5, v6
	v_and_b32_e32 v15, 32, v3
	v_bfe_i32 v16, v0, 0, 16
	s_mul_hi_i32 s8, s93, s8
	s_add_u32 s74, s38, s9
	v_mul_lo_u32 v2, s5, v2
	v_add_u32_e32 v0, v15, v16
	s_addc_u32 s75, s39, s8
	s_add_i32 s97, s94, 0
	v_add_lshl_u32 v192, v2, v0, 1
	s_add_i32 m0, s97, 0x10000
	v_readlane_b32 s3, v254, 16
	global_load_lds_dwordx4 v192, s[74:75]
	s_add_i32 m0, s97, 0x12000
	s_add_u32 s8, s74, s12
	global_load_lds_dwordx4 v198, s[74:75]
	s_addc_u32 s9, s75, 0
	s_add_i32 m0, s97, 0x14000
	s_mul_i32 s11, s93, s3
	global_load_lds_dwordx4 v192, s[8:9]
	s_add_i32 m0, s97, 0x16000
	s_mul_hi_i32 s10, s93, s3
	s_add_u32 s80, s96, s11
	v_mul_lo_u32 v17, s5, v4
	v_mov_b32_e32 v199, v193
	s_addc_u32 s81, s95, s10
	s_add_i32 s98, s97, 0x2000
	s_waitcnt lgkmcnt(0)
	v_add_lshl_u32 v202, v17, v0, 1
	v_lshl_add_u64 v[4:5], s[8:9], 0, v[192:193]
	v_lshl_add_u64 v[6:7], s[8:9], 0, v[198:199]
	global_load_lds_dwordx4 v198, s[8:9]
	s_mov_b32 m0, s97
	s_add_u32 s8, s80, s12
	global_load_lds_dwordx4 v202, s[80:81]
	s_mov_b32 m0, s98
	s_addc_u32 s9, s81, 0
	s_add_i32 s99, s97, 0x4000
	global_load_lds_dwordx4 v200, s[80:81]
	s_mov_b32 m0, s99
	s_add_i32 s78, s97, 0x6000
	global_load_lds_dwordx4 v202, s[8:9]
	s_mov_b32 m0, s78
	v_mov_b32_e32 v203, v193
	global_load_lds_dwordx4 v200, s[8:9]
	v_mov_b32_e32 v201, v193
	s_cmp_eq_u32 s6, 1
	v_lshl_add_u64 v[0:1], s[74:75], 0, v[192:193]
	v_lshl_add_u64 v[2:3], s[74:75], 0, v[198:199]
	v_lshl_add_u64 v[8:9], s[80:81], 0, v[202:203]
	v_lshl_add_u64 v[10:11], s[80:81], 0, v[200:201]
	s_cselect_b64 s[22:23], -1, 0
	s_setprio 1
	s_cmp_lg_u32 s6, 1
	s_cbranch_scc1 .LBB0_549
	s_barrier
	s_setprio 0
